# P2 prompt forget cumsum (scan_seq<32>): hand-written DPP prefix scan instead of 198 serialized ds_bpermute hops
# speedup vs baseline: 1.0088x; 1.0088x over previous
.LBB0_655:
	s_or_b64 exec, exec, s[12:13]
	v_and_b32_e32 v2, 0xc0, v0
	v_cmp_eq_u32_e32 vcc, 0, v2
	v_ashrrev_i32_e32 v2, 2, v22
	s_movk_i32 s2, 0x140
	v_cmp_gt_i32_e64 s[6:7], s2, v2
	s_and_b64 s[2:3], vcc, s[6:7]
	s_and_saveexec_b64 s[22:23], s[2:3]
	s_cbranch_execz .LBB0_728
	s_load_dwordx16 s[36:51], s[62:63], 0x80
	s_add_u32 s24, s34, 0x1c00000
	s_addc_u32 s25, s35, 0
	s_ashr_i32 s0, s0, 2
	v_ashrrev_i32_e32 v3, 31, v2
	s_waitcnt lgkmcnt(0)
	s_add_u32 s26, s50, 0xa2d8000
	s_addc_u32 s27, s51, 0
	v_lshlrev_b64 v[8:9], 13, v[2:3]
	s_add_u32 s28, s50, 0x8800000
	v_or_b32_e32 v8, v8, v18
	s_addc_u32 s29, s51, 0
	v_lshl_add_u64 v[8:9], s[34:35], 0, v[8:9]
	s_mov_b64 s[2:3], 0x2100000
	s_lshl_b32 s1, s1, 1
	v_mbcnt_lo_u32_b32 v3, -1, 0
	v_mov_b32_e32 v7, 0
	v_lshl_add_u32 v12, v137, 14, 0
	v_lshl_add_u64 v[8:9], v[8:9], 0, s[2:3]
	s_bfe_i32 s3, s1, 0x1001d
	s_bfe_i32 s2, s1, 0x1e0000
	v_mbcnt_hi_u32_b32 v3, -1, v3
	v_lshlrev_b32_e32 v4, 5, v1
	v_mov_b32_e32 v5, v7
	v_cmp_eq_u32_e64 s[6:7], 0, v1
	v_cmp_gt_u32_e64 s[8:9], 2, v1
	v_cmp_gt_u32_e64 s[10:11], 4, v1
	v_cmp_gt_u32_e64 s[12:13], 8, v1
	v_cmp_gt_u32_e64 s[14:15], 16, v1
	v_cmp_gt_u32_e64 s[16:17], 32, v1
	v_cmp_eq_u32_e64 s[18:19], 63, v1
	v_add_u32_e32 v1, v12, v18
	s_lshl_b64 s[30:31], s[2:3], 13
	s_mov_b64 s[36:37], 0
	s_movk_i32 s1, 0x4100
	s_movk_i32 s2, 0x3000
	s_movk_i32 s3, 0x4000
	v_lshlrev_b32_e32 v10, 2, v20
	s_movk_i32 s4, 0x1000
	s_movk_i32 s5, 0x13f
	v_and_b32_e32 v13, 64, v3
	v_add_u32_e32 v14, -1, v3
	v_add_u32_e32 v15, -2, v3
	v_add_u32_e32 v16, -4, v3
	v_add_u32_e32 v17, -8, v3
	v_add_u32_e32 v20, -16, v3
	v_subrev_u32_e32 v21, 32, v3
	s_branch .LBB0_659
.LBB0_658:
	s_or_b64 exec, exec, s[40:41]
	v_add_u32_e32 v2, s0, v2
	v_cmp_lt_i32_e32 vcc, s5, v2
	s_or_b64 s[36:37], vcc, s[36:37]
	v_lshl_add_u64 v[8:9], v[8:9], 0, s[30:31]
	s_andn2_b64 exec, exec, s[36:37]
	s_cbranch_execz .LBB0_728

.LBB0_661:
	s_andn2_saveexec_b64 s[40:41], s[40:41]
	s_cbranch_execz .LBB0_658
	v_ashrrev_i32_e32 v22, 3, v2
	v_ashrrev_i32_e32 v23, 31, v22
	v_lshlrev_b64 v[22:23], 16, v[22:23]
	v_lshl_add_u64 v[22:23], s[28:29], 0, v[22:23]
	v_lshl_add_u64 v[22:23], v[22:23], 0, v[6:7]
	v_mov_b32_e32 v11, v7
	v_lshl_add_u64 v[22:23], v[22:23], 0, v[10:11]
	s_mov_b64 s[42:43], 0x1000
	s_mov_b64 s[46:47], exec
	global_load_dword v32, v[22:23], off
	global_load_dword v33, v[22:23], off offset:2048
	v_lshl_add_u64 v[22:23], v[22:23], 0, s[42:43]
	global_load_dword v34, v[22:23], off
	global_load_dword v35, v[22:23], off offset:2048
	v_lshl_add_u64 v[22:23], v[22:23], 0, s[42:43]
	global_load_dword v36, v[22:23], off
	global_load_dword v37, v[22:23], off offset:2048
	v_lshl_add_u64 v[22:23], v[22:23], 0, s[42:43]
	global_load_dword v38, v[22:23], off
	global_load_dword v39, v[22:23], off offset:2048
	v_lshl_add_u64 v[22:23], v[22:23], 0, s[42:43]
	global_load_dword v40, v[22:23], off
	global_load_dword v41, v[22:23], off offset:2048
	v_lshl_add_u64 v[22:23], v[22:23], 0, s[42:43]
	global_load_dword v42, v[22:23], off
	global_load_dword v43, v[22:23], off offset:2048
	v_lshl_add_u64 v[22:23], v[22:23], 0, s[42:43]
	global_load_dword v44, v[22:23], off
	global_load_dword v45, v[22:23], off offset:2048
	v_lshl_add_u64 v[22:23], v[22:23], 0, s[42:43]
	global_load_dword v46, v[22:23], off
	global_load_dword v47, v[22:23], off offset:2048
	v_lshl_add_u64 v[22:23], v[22:23], 0, s[42:43]
	global_load_dword v48, v[22:23], off
	global_load_dword v49, v[22:23], off offset:2048
	v_lshl_add_u64 v[22:23], v[22:23], 0, s[42:43]
	global_load_dword v50, v[22:23], off
	global_load_dword v51, v[22:23], off offset:2048
	v_lshl_add_u64 v[22:23], v[22:23], 0, s[42:43]
	global_load_dword v52, v[22:23], off
	global_load_dword v53, v[22:23], off offset:2048
	v_lshl_add_u64 v[22:23], v[22:23], 0, s[42:43]
	global_load_dword v54, v[22:23], off
	global_load_dword v55, v[22:23], off offset:2048
	v_lshl_add_u64 v[22:23], v[22:23], 0, s[42:43]
	global_load_dword v56, v[22:23], off
	global_load_dword v57, v[22:23], off offset:2048
	v_lshl_add_u64 v[22:23], v[22:23], 0, s[42:43]
	global_load_dword v58, v[22:23], off
	global_load_dword v59, v[22:23], off offset:2048
	v_lshl_add_u64 v[22:23], v[22:23], 0, s[42:43]
	global_load_dword v60, v[22:23], off
	global_load_dword v61, v[22:23], off offset:2048
	v_lshl_add_u64 v[22:23], v[22:23], 0, s[42:43]
	global_load_dword v62, v[22:23], off
	global_load_dword v63, v[22:23], off offset:2048
	s_waitcnt vmcnt(24)
	v_add_f32_dpp v32, v32, v32 row_shr:1 row_mask:0xf bank_mask:0xf
	v_add_f32_dpp v33, v33, v33 row_shr:1 row_mask:0xf bank_mask:0xf
	v_add_f32_dpp v34, v34, v34 row_shr:1 row_mask:0xf bank_mask:0xf
	v_add_f32_dpp v35, v35, v35 row_shr:1 row_mask:0xf bank_mask:0xf
	v_add_f32_dpp v36, v36, v36 row_shr:1 row_mask:0xf bank_mask:0xf
	v_add_f32_dpp v37, v37, v37 row_shr:1 row_mask:0xf bank_mask:0xf
	v_add_f32_dpp v38, v38, v38 row_shr:1 row_mask:0xf bank_mask:0xf
	v_add_f32_dpp v39, v39, v39 row_shr:1 row_mask:0xf bank_mask:0xf
	v_add_f32_dpp v32, v32, v32 row_shr:2 row_mask:0xf bank_mask:0xf
	v_add_f32_dpp v33, v33, v33 row_shr:2 row_mask:0xf bank_mask:0xf
	v_add_f32_dpp v34, v34, v34 row_shr:2 row_mask:0xf bank_mask:0xf
	v_add_f32_dpp v35, v35, v35 row_shr:2 row_mask:0xf bank_mask:0xf
	v_add_f32_dpp v36, v36, v36 row_shr:2 row_mask:0xf bank_mask:0xf
	v_add_f32_dpp v37, v37, v37 row_shr:2 row_mask:0xf bank_mask:0xf
	v_add_f32_dpp v38, v38, v38 row_shr:2 row_mask:0xf bank_mask:0xf
	v_add_f32_dpp v39, v39, v39 row_shr:2 row_mask:0xf bank_mask:0xf
	v_add_f32_dpp v32, v32, v32 row_shr:4 row_mask:0xf bank_mask:0xf
	v_add_f32_dpp v33, v33, v33 row_shr:4 row_mask:0xf bank_mask:0xf
	v_add_f32_dpp v34, v34, v34 row_shr:4 row_mask:0xf bank_mask:0xf
	v_add_f32_dpp v35, v35, v35 row_shr:4 row_mask:0xf bank_mask:0xf
	v_add_f32_dpp v36, v36, v36 row_shr:4 row_mask:0xf bank_mask:0xf
	v_add_f32_dpp v37, v37, v37 row_shr:4 row_mask:0xf bank_mask:0xf
	v_add_f32_dpp v38, v38, v38 row_shr:4 row_mask:0xf bank_mask:0xf
	v_add_f32_dpp v39, v39, v39 row_shr:4 row_mask:0xf bank_mask:0xf
	v_add_f32_dpp v32, v32, v32 row_shr:8 row_mask:0xf bank_mask:0xf
	v_add_f32_dpp v33, v33, v33 row_shr:8 row_mask:0xf bank_mask:0xf
	v_add_f32_dpp v34, v34, v34 row_shr:8 row_mask:0xf bank_mask:0xf
	v_add_f32_dpp v35, v35, v35 row_shr:8 row_mask:0xf bank_mask:0xf
	v_add_f32_dpp v36, v36, v36 row_shr:8 row_mask:0xf bank_mask:0xf
	v_add_f32_dpp v37, v37, v37 row_shr:8 row_mask:0xf bank_mask:0xf
	v_add_f32_dpp v38, v38, v38 row_shr:8 row_mask:0xf bank_mask:0xf
	v_add_f32_dpp v39, v39, v39 row_shr:8 row_mask:0xf bank_mask:0xf
	v_add_f32_dpp v32, v32, v32 row_bcast:15 row_mask:0xa bank_mask:0xf
	v_add_f32_dpp v33, v33, v33 row_bcast:15 row_mask:0xa bank_mask:0xf
	v_add_f32_dpp v34, v34, v34 row_bcast:15 row_mask:0xa bank_mask:0xf
	v_add_f32_dpp v35, v35, v35 row_bcast:15 row_mask:0xa bank_mask:0xf
	v_add_f32_dpp v36, v36, v36 row_bcast:15 row_mask:0xa bank_mask:0xf
	v_add_f32_dpp v37, v37, v37 row_bcast:15 row_mask:0xa bank_mask:0xf
	v_add_f32_dpp v38, v38, v38 row_bcast:15 row_mask:0xa bank_mask:0xf
	v_add_f32_dpp v39, v39, v39 row_bcast:15 row_mask:0xa bank_mask:0xf
	v_add_f32_dpp v32, v32, v32 row_bcast:31 row_mask:0xc bank_mask:0xf
	v_add_f32_dpp v33, v33, v33 row_bcast:31 row_mask:0xc bank_mask:0xf
	v_add_f32_dpp v34, v34, v34 row_bcast:31 row_mask:0xc bank_mask:0xf
	v_add_f32_dpp v35, v35, v35 row_bcast:31 row_mask:0xc bank_mask:0xf
	v_add_f32_dpp v36, v36, v36 row_bcast:31 row_mask:0xc bank_mask:0xf
	v_add_f32_dpp v37, v37, v37 row_bcast:31 row_mask:0xc bank_mask:0xf
	v_add_f32_dpp v38, v38, v38 row_bcast:31 row_mask:0xc bank_mask:0xf
	v_add_f32_dpp v39, v39, v39 row_bcast:31 row_mask:0xc bank_mask:0xf
	s_waitcnt vmcnt(16)
	v_add_f32_dpp v40, v40, v40 row_shr:1 row_mask:0xf bank_mask:0xf
	v_add_f32_dpp v41, v41, v41 row_shr:1 row_mask:0xf bank_mask:0xf
	v_add_f32_dpp v42, v42, v42 row_shr:1 row_mask:0xf bank_mask:0xf
	v_add_f32_dpp v43, v43, v43 row_shr:1 row_mask:0xf bank_mask:0xf
	v_add_f32_dpp v44, v44, v44 row_shr:1 row_mask:0xf bank_mask:0xf
	v_add_f32_dpp v45, v45, v45 row_shr:1 row_mask:0xf bank_mask:0xf
	v_add_f32_dpp v46, v46, v46 row_shr:1 row_mask:0xf bank_mask:0xf
	v_add_f32_dpp v47, v47, v47 row_shr:1 row_mask:0xf bank_mask:0xf
	v_add_f32_dpp v40, v40, v40 row_shr:2 row_mask:0xf bank_mask:0xf
	v_add_f32_dpp v41, v41, v41 row_shr:2 row_mask:0xf bank_mask:0xf
	v_add_f32_dpp v42, v42, v42 row_shr:2 row_mask:0xf bank_mask:0xf
	v_add_f32_dpp v43, v43, v43 row_shr:2 row_mask:0xf bank_mask:0xf
	v_add_f32_dpp v44, v44, v44 row_shr:2 row_mask:0xf bank_mask:0xf
	v_add_f32_dpp v45, v45, v45 row_shr:2 row_mask:0xf bank_mask:0xf
	v_add_f32_dpp v46, v46, v46 row_shr:2 row_mask:0xf bank_mask:0xf
	v_add_f32_dpp v47, v47, v47 row_shr:2 row_mask:0xf bank_mask:0xf
	v_add_f32_dpp v40, v40, v40 row_shr:4 row_mask:0xf bank_mask:0xf
	v_add_f32_dpp v41, v41, v41 row_shr:4 row_mask:0xf bank_mask:0xf
	v_add_f32_dpp v42, v42, v42 row_shr:4 row_mask:0xf bank_mask:0xf
	v_add_f32_dpp v43, v43, v43 row_shr:4 row_mask:0xf bank_mask:0xf
	v_add_f32_dpp v44, v44, v44 row_shr:4 row_mask:0xf bank_mask:0xf
	v_add_f32_dpp v45, v45, v45 row_shr:4 row_mask:0xf bank_mask:0xf
	v_add_f32_dpp v46, v46, v46 row_shr:4 row_mask:0xf bank_mask:0xf
	v_add_f32_dpp v47, v47, v47 row_shr:4 row_mask:0xf bank_mask:0xf
	v_add_f32_dpp v40, v40, v40 row_shr:8 row_mask:0xf bank_mask:0xf
	v_add_f32_dpp v41, v41, v41 row_shr:8 row_mask:0xf bank_mask:0xf
	v_add_f32_dpp v42, v42, v42 row_shr:8 row_mask:0xf bank_mask:0xf
	v_add_f32_dpp v43, v43, v43 row_shr:8 row_mask:0xf bank_mask:0xf
	v_add_f32_dpp v44, v44, v44 row_shr:8 row_mask:0xf bank_mask:0xf
	v_add_f32_dpp v45, v45, v45 row_shr:8 row_mask:0xf bank_mask:0xf
	v_add_f32_dpp v46, v46, v46 row_shr:8 row_mask:0xf bank_mask:0xf
	v_add_f32_dpp v47, v47, v47 row_shr:8 row_mask:0xf bank_mask:0xf
	v_add_f32_dpp v40, v40, v40 row_bcast:15 row_mask:0xa bank_mask:0xf
	v_add_f32_dpp v41, v41, v41 row_bcast:15 row_mask:0xa bank_mask:0xf
	v_add_f32_dpp v42, v42, v42 row_bcast:15 row_mask:0xa bank_mask:0xf
	v_add_f32_dpp v43, v43, v43 row_bcast:15 row_mask:0xa bank_mask:0xf
	v_add_f32_dpp v44, v44, v44 row_bcast:15 row_mask:0xa bank_mask:0xf
	v_add_f32_dpp v45, v45, v45 row_bcast:15 row_mask:0xa bank_mask:0xf
	v_add_f32_dpp v46, v46, v46 row_bcast:15 row_mask:0xa bank_mask:0xf
	v_add_f32_dpp v47, v47, v47 row_bcast:15 row_mask:0xa bank_mask:0xf
	v_add_f32_dpp v40, v40, v40 row_bcast:31 row_mask:0xc bank_mask:0xf
	v_add_f32_dpp v41, v41, v41 row_bcast:31 row_mask:0xc bank_mask:0xf
	v_add_f32_dpp v42, v42, v42 row_bcast:31 row_mask:0xc bank_mask:0xf
	v_add_f32_dpp v43, v43, v43 row_bcast:31 row_mask:0xc bank_mask:0xf
	v_add_f32_dpp v44, v44, v44 row_bcast:31 row_mask:0xc bank_mask:0xf
	v_add_f32_dpp v45, v45, v45 row_bcast:31 row_mask:0xc bank_mask:0xf
	v_add_f32_dpp v46, v46, v46 row_bcast:31 row_mask:0xc bank_mask:0xf
	v_add_f32_dpp v47, v47, v47 row_bcast:31 row_mask:0xc bank_mask:0xf
	s_waitcnt vmcnt(8)
	v_add_f32_dpp v48, v48, v48 row_shr:1 row_mask:0xf bank_mask:0xf
	v_add_f32_dpp v49, v49, v49 row_shr:1 row_mask:0xf bank_mask:0xf
	v_add_f32_dpp v50, v50, v50 row_shr:1 row_mask:0xf bank_mask:0xf
	v_add_f32_dpp v51, v51, v51 row_shr:1 row_mask:0xf bank_mask:0xf
	v_add_f32_dpp v52, v52, v52 row_shr:1 row_mask:0xf bank_mask:0xf
	v_add_f32_dpp v53, v53, v53 row_shr:1 row_mask:0xf bank_mask:0xf
	v_add_f32_dpp v54, v54, v54 row_shr:1 row_mask:0xf bank_mask:0xf
	v_add_f32_dpp v55, v55, v55 row_shr:1 row_mask:0xf bank_mask:0xf
	v_add_f32_dpp v48, v48, v48 row_shr:2 row_mask:0xf bank_mask:0xf
	v_add_f32_dpp v49, v49, v49 row_shr:2 row_mask:0xf bank_mask:0xf
	v_add_f32_dpp v50, v50, v50 row_shr:2 row_mask:0xf bank_mask:0xf
	v_add_f32_dpp v51, v51, v51 row_shr:2 row_mask:0xf bank_mask:0xf
	v_add_f32_dpp v52, v52, v52 row_shr:2 row_mask:0xf bank_mask:0xf
	v_add_f32_dpp v53, v53, v53 row_shr:2 row_mask:0xf bank_mask:0xf
	v_add_f32_dpp v54, v54, v54 row_shr:2 row_mask:0xf bank_mask:0xf
	v_add_f32_dpp v55, v55, v55 row_shr:2 row_mask:0xf bank_mask:0xf
	v_add_f32_dpp v48, v48, v48 row_shr:4 row_mask:0xf bank_mask:0xf
	v_add_f32_dpp v49, v49, v49 row_shr:4 row_mask:0xf bank_mask:0xf
	v_add_f32_dpp v50, v50, v50 row_shr:4 row_mask:0xf bank_mask:0xf
	v_add_f32_dpp v51, v51, v51 row_shr:4 row_mask:0xf bank_mask:0xf
	v_add_f32_dpp v52, v52, v52 row_shr:4 row_mask:0xf bank_mask:0xf
	v_add_f32_dpp v53, v53, v53 row_shr:4 row_mask:0xf bank_mask:0xf
	v_add_f32_dpp v54, v54, v54 row_shr:4 row_mask:0xf bank_mask:0xf
	v_add_f32_dpp v55, v55, v55 row_shr:4 row_mask:0xf bank_mask:0xf
	v_add_f32_dpp v48, v48, v48 row_shr:8 row_mask:0xf bank_mask:0xf
	v_add_f32_dpp v49, v49, v49 row_shr:8 row_mask:0xf bank_mask:0xf
	v_add_f32_dpp v50, v50, v50 row_shr:8 row_mask:0xf bank_mask:0xf
	v_add_f32_dpp v51, v51, v51 row_shr:8 row_mask:0xf bank_mask:0xf
	v_add_f32_dpp v52, v52, v52 row_shr:8 row_mask:0xf bank_mask:0xf
	v_add_f32_dpp v53, v53, v53 row_shr:8 row_mask:0xf bank_mask:0xf
	v_add_f32_dpp v54, v54, v54 row_shr:8 row_mask:0xf bank_mask:0xf
	v_add_f32_dpp v55, v55, v55 row_shr:8 row_mask:0xf bank_mask:0xf
	v_add_f32_dpp v48, v48, v48 row_bcast:15 row_mask:0xa bank_mask:0xf
	v_add_f32_dpp v49, v49, v49 row_bcast:15 row_mask:0xa bank_mask:0xf
	v_add_f32_dpp v50, v50, v50 row_bcast:15 row_mask:0xa bank_mask:0xf
	v_add_f32_dpp v51, v51, v51 row_bcast:15 row_mask:0xa bank_mask:0xf
	v_add_f32_dpp v52, v52, v52 row_bcast:15 row_mask:0xa bank_mask:0xf
	v_add_f32_dpp v53, v53, v53 row_bcast:15 row_mask:0xa bank_mask:0xf
	v_add_f32_dpp v54, v54, v54 row_bcast:15 row_mask:0xa bank_mask:0xf
	v_add_f32_dpp v55, v55, v55 row_bcast:15 row_mask:0xa bank_mask:0xf
	v_add_f32_dpp v48, v48, v48 row_bcast:31 row_mask:0xc bank_mask:0xf
	v_add_f32_dpp v49, v49, v49 row_bcast:31 row_mask:0xc bank_mask:0xf
	v_add_f32_dpp v50, v50, v50 row_bcast:31 row_mask:0xc bank_mask:0xf
	v_add_f32_dpp v51, v51, v51 row_bcast:31 row_mask:0xc bank_mask:0xf
	v_add_f32_dpp v52, v52, v52 row_bcast:31 row_mask:0xc bank_mask:0xf
	v_add_f32_dpp v53, v53, v53 row_bcast:31 row_mask:0xc bank_mask:0xf
	v_add_f32_dpp v54, v54, v54 row_bcast:31 row_mask:0xc bank_mask:0xf
	v_add_f32_dpp v55, v55, v55 row_bcast:31 row_mask:0xc bank_mask:0xf
	s_waitcnt vmcnt(0)
	v_add_f32_dpp v56, v56, v56 row_shr:1 row_mask:0xf bank_mask:0xf
	v_add_f32_dpp v57, v57, v57 row_shr:1 row_mask:0xf bank_mask:0xf
	v_add_f32_dpp v58, v58, v58 row_shr:1 row_mask:0xf bank_mask:0xf
	v_add_f32_dpp v59, v59, v59 row_shr:1 row_mask:0xf bank_mask:0xf
	v_add_f32_dpp v60, v60, v60 row_shr:1 row_mask:0xf bank_mask:0xf
	v_add_f32_dpp v61, v61, v61 row_shr:1 row_mask:0xf bank_mask:0xf
	v_add_f32_dpp v62, v62, v62 row_shr:1 row_mask:0xf bank_mask:0xf
	v_add_f32_dpp v63, v63, v63 row_shr:1 row_mask:0xf bank_mask:0xf
	v_add_f32_dpp v56, v56, v56 row_shr:2 row_mask:0xf bank_mask:0xf
	v_add_f32_dpp v57, v57, v57 row_shr:2 row_mask:0xf bank_mask:0xf
	v_add_f32_dpp v58, v58, v58 row_shr:2 row_mask:0xf bank_mask:0xf
	v_add_f32_dpp v59, v59, v59 row_shr:2 row_mask:0xf bank_mask:0xf
	v_add_f32_dpp v60, v60, v60 row_shr:2 row_mask:0xf bank_mask:0xf
	v_add_f32_dpp v61, v61, v61 row_shr:2 row_mask:0xf bank_mask:0xf
	v_add_f32_dpp v62, v62, v62 row_shr:2 row_mask:0xf bank_mask:0xf
	v_add_f32_dpp v63, v63, v63 row_shr:2 row_mask:0xf bank_mask:0xf
	v_add_f32_dpp v56, v56, v56 row_shr:4 row_mask:0xf bank_mask:0xf
	v_add_f32_dpp v57, v57, v57 row_shr:4 row_mask:0xf bank_mask:0xf
	v_add_f32_dpp v58, v58, v58 row_shr:4 row_mask:0xf bank_mask:0xf
	v_add_f32_dpp v59, v59, v59 row_shr:4 row_mask:0xf bank_mask:0xf
	v_add_f32_dpp v60, v60, v60 row_shr:4 row_mask:0xf bank_mask:0xf
	v_add_f32_dpp v61, v61, v61 row_shr:4 row_mask:0xf bank_mask:0xf
	v_add_f32_dpp v62, v62, v62 row_shr:4 row_mask:0xf bank_mask:0xf
	v_add_f32_dpp v63, v63, v63 row_shr:4 row_mask:0xf bank_mask:0xf
	v_add_f32_dpp v56, v56, v56 row_shr:8 row_mask:0xf bank_mask:0xf
	v_add_f32_dpp v57, v57, v57 row_shr:8 row_mask:0xf bank_mask:0xf
	v_add_f32_dpp v58, v58, v58 row_shr:8 row_mask:0xf bank_mask:0xf
	v_add_f32_dpp v59, v59, v59 row_shr:8 row_mask:0xf bank_mask:0xf
	v_add_f32_dpp v60, v60, v60 row_shr:8 row_mask:0xf bank_mask:0xf
	v_add_f32_dpp v61, v61, v61 row_shr:8 row_mask:0xf bank_mask:0xf
	v_add_f32_dpp v62, v62, v62 row_shr:8 row_mask:0xf bank_mask:0xf
	v_add_f32_dpp v63, v63, v63 row_shr:8 row_mask:0xf bank_mask:0xf
	v_add_f32_dpp v56, v56, v56 row_bcast:15 row_mask:0xa bank_mask:0xf
	v_add_f32_dpp v57, v57, v57 row_bcast:15 row_mask:0xa bank_mask:0xf
	v_add_f32_dpp v58, v58, v58 row_bcast:15 row_mask:0xa bank_mask:0xf
	v_add_f32_dpp v59, v59, v59 row_bcast:15 row_mask:0xa bank_mask:0xf
	v_add_f32_dpp v60, v60, v60 row_bcast:15 row_mask:0xa bank_mask:0xf
	v_add_f32_dpp v61, v61, v61 row_bcast:15 row_mask:0xa bank_mask:0xf
	v_add_f32_dpp v62, v62, v62 row_bcast:15 row_mask:0xa bank_mask:0xf
	v_add_f32_dpp v63, v63, v63 row_bcast:15 row_mask:0xa bank_mask:0xf
	v_add_f32_dpp v56, v56, v56 row_bcast:31 row_mask:0xc bank_mask:0xf
	v_add_f32_dpp v57, v57, v57 row_bcast:31 row_mask:0xc bank_mask:0xf
	v_add_f32_dpp v58, v58, v58 row_bcast:31 row_mask:0xc bank_mask:0xf
	v_add_f32_dpp v59, v59, v59 row_bcast:31 row_mask:0xc bank_mask:0xf
	v_add_f32_dpp v60, v60, v60 row_bcast:31 row_mask:0xc bank_mask:0xf
	v_add_f32_dpp v61, v61, v61 row_bcast:31 row_mask:0xc bank_mask:0xf
	v_add_f32_dpp v62, v62, v62 row_bcast:31 row_mask:0xc bank_mask:0xf
	v_add_f32_dpp v63, v63, v63 row_bcast:31 row_mask:0xc bank_mask:0xf
	s_mov_b32 exec_lo, 0
	s_brev_b32 exec_hi, 1
	ds_write_b32 v12, v32
	ds_write_b32 v12, v33 offset:4
	ds_write_b32 v12, v34 offset:8
	ds_write_b32 v12, v35 offset:12
	ds_write_b32 v12, v36 offset:16
	ds_write_b32 v12, v37 offset:20
	ds_write_b32 v12, v38 offset:24
	ds_write_b32 v12, v39 offset:28
	ds_write_b32 v12, v40 offset:32
	ds_write_b32 v12, v41 offset:36
	ds_write_b32 v12, v42 offset:40
	ds_write_b32 v12, v43 offset:44
	ds_write_b32 v12, v44 offset:48
	ds_write_b32 v12, v45 offset:52
	ds_write_b32 v12, v46 offset:56
	ds_write_b32 v12, v47 offset:60
	ds_write_b32 v12, v48 offset:64
	ds_write_b32 v12, v49 offset:68
	ds_write_b32 v12, v50 offset:72
	ds_write_b32 v12, v51 offset:76
	ds_write_b32 v12, v52 offset:80
	ds_write_b32 v12, v53 offset:84
	ds_write_b32 v12, v54 offset:88
	ds_write_b32 v12, v55 offset:92
	ds_write_b32 v12, v56 offset:96
	ds_write_b32 v12, v57 offset:100
	ds_write_b32 v12, v58 offset:104
	ds_write_b32 v12, v59 offset:108
	ds_write_b32 v12, v60 offset:112
	ds_write_b32 v12, v61 offset:116
	ds_write_b32 v12, v62 offset:120
	ds_write_b32 v12, v63 offset:124
	s_mov_b64 exec, s[46:47]
	s_waitcnt lgkmcnt(0)
	v_mov_b32_e32 v64, 0
	s_and_saveexec_b64 s[38:39], s[16:17]
	ds_read_b32 v64, v1
	s_mov_b64 exec, s[46:47]
	s_waitcnt lgkmcnt(0)
	s_nop 1
	v_add_f32_dpp v64, v64, v64 row_shr:1 row_mask:0xf bank_mask:0xf
	s_nop 1
	v_add_f32_dpp v64, v64, v64 row_shr:2 row_mask:0xf bank_mask:0xf
	s_nop 1
	v_add_f32_dpp v64, v64, v64 row_shr:4 row_mask:0xf bank_mask:0xf
	s_nop 1
	v_add_f32_dpp v64, v64, v64 row_shr:8 row_mask:0xf bank_mask:0xf
	s_nop 1
	v_add_f32_dpp v64, v64, v64 row_bcast:15 row_mask:0xa bank_mask:0xf
	s_nop 1
	v_add_f32_dpp v64, v64, v64 row_bcast:31 row_mask:0xc bank_mask:0xf
	s_nop 1
	v_readlane_b32 s38, v64, 0
	v_readlane_b32 s33, v64, 1
	v_lshl_add_u64 v[22:23], v[8:9], 0, s[42:43]
	s_nop 0
	v_mul_f32_e32 v32, 0x3fb8aa3b, v32
	global_store_dword v[8:9], v32, off
	v_add_f32_e32 v33, s38, v33
	v_readlane_b32 s38, v64, 2
	v_mul_f32_e32 v33, 0x3fb8aa3b, v33
	global_store_dword v[8:9], v33, off offset:256
	v_add_f32_e32 v34, s33, v34
	v_readlane_b32 s33, v64, 3
	v_mul_f32_e32 v34, 0x3fb8aa3b, v34
	global_store_dword v[8:9], v34, off offset:512
	v_add_f32_e32 v35, s38, v35
	v_readlane_b32 s38, v64, 4
	v_mul_f32_e32 v35, 0x3fb8aa3b, v35
	global_store_dword v[8:9], v35, off offset:768
	v_add_f32_e32 v36, s33, v36
	v_readlane_b32 s33, v64, 5
	v_mul_f32_e32 v36, 0x3fb8aa3b, v36
	global_store_dword v[8:9], v36, off offset:1024
	v_add_f32_e32 v37, s38, v37
	v_readlane_b32 s38, v64, 6
	v_mul_f32_e32 v37, 0x3fb8aa3b, v37
	global_store_dword v[8:9], v37, off offset:1280
	v_add_f32_e32 v38, s33, v38
	v_readlane_b32 s33, v64, 7
	v_mul_f32_e32 v38, 0x3fb8aa3b, v38
	global_store_dword v[8:9], v38, off offset:1536
	v_add_f32_e32 v39, s38, v39
	v_readlane_b32 s38, v64, 8
	v_mul_f32_e32 v39, 0x3fb8aa3b, v39
	global_store_dword v[8:9], v39, off offset:1792
	v_add_f32_e32 v40, s33, v40
	v_readlane_b32 s33, v64, 9
	v_mul_f32_e32 v40, 0x3fb8aa3b, v40
	global_store_dword v[8:9], v40, off offset:2048
	v_add_f32_e32 v41, s38, v41
	v_readlane_b32 s38, v64, 10
	v_mul_f32_e32 v41, 0x3fb8aa3b, v41
	global_store_dword v[8:9], v41, off offset:2304
	v_add_f32_e32 v42, s33, v42
	v_readlane_b32 s33, v64, 11
	v_mul_f32_e32 v42, 0x3fb8aa3b, v42
	global_store_dword v[8:9], v42, off offset:2560
	v_add_f32_e32 v43, s38, v43
	v_readlane_b32 s38, v64, 12
	v_mul_f32_e32 v43, 0x3fb8aa3b, v43
	global_store_dword v[8:9], v43, off offset:2816
	v_add_f32_e32 v44, s33, v44
	v_readlane_b32 s33, v64, 13
	v_mul_f32_e32 v44, 0x3fb8aa3b, v44
	global_store_dword v[8:9], v44, off offset:3072
	v_add_f32_e32 v45, s38, v45
	v_readlane_b32 s38, v64, 14
	v_mul_f32_e32 v45, 0x3fb8aa3b, v45
	global_store_dword v[8:9], v45, off offset:3328
	v_add_f32_e32 v46, s33, v46
	v_readlane_b32 s33, v64, 15
	v_mul_f32_e32 v46, 0x3fb8aa3b, v46
	global_store_dword v[8:9], v46, off offset:3584
	v_add_f32_e32 v47, s38, v47
	v_readlane_b32 s38, v64, 16
	v_mul_f32_e32 v47, 0x3fb8aa3b, v47
	global_store_dword v[8:9], v47, off offset:3840
	v_add_f32_e32 v48, s33, v48
	v_readlane_b32 s33, v64, 17
	v_mul_f32_e32 v48, 0x3fb8aa3b, v48
	global_store_dword v[22:23], v48, off
	v_add_f32_e32 v49, s38, v49
	v_readlane_b32 s38, v64, 18
	v_mul_f32_e32 v49, 0x3fb8aa3b, v49
	global_store_dword v[22:23], v49, off offset:256
	v_add_f32_e32 v50, s33, v50
	v_readlane_b32 s33, v64, 19
	v_mul_f32_e32 v50, 0x3fb8aa3b, v50
	global_store_dword v[22:23], v50, off offset:512
	v_add_f32_e32 v51, s38, v51
	v_readlane_b32 s38, v64, 20
	v_mul_f32_e32 v51, 0x3fb8aa3b, v51
	global_store_dword v[22:23], v51, off offset:768
	v_add_f32_e32 v52, s33, v52
	v_readlane_b32 s33, v64, 21
	v_mul_f32_e32 v52, 0x3fb8aa3b, v52
	global_store_dword v[22:23], v52, off offset:1024
	v_add_f32_e32 v53, s38, v53
	v_readlane_b32 s38, v64, 22
	v_mul_f32_e32 v53, 0x3fb8aa3b, v53
	global_store_dword v[22:23], v53, off offset:1280
	v_add_f32_e32 v54, s33, v54
	v_readlane_b32 s33, v64, 23
	v_mul_f32_e32 v54, 0x3fb8aa3b, v54
	global_store_dword v[22:23], v54, off offset:1536
	v_add_f32_e32 v55, s38, v55
	v_readlane_b32 s38, v64, 24
	v_mul_f32_e32 v55, 0x3fb8aa3b, v55
	global_store_dword v[22:23], v55, off offset:1792
	v_add_f32_e32 v56, s33, v56
	v_readlane_b32 s33, v64, 25
	v_mul_f32_e32 v56, 0x3fb8aa3b, v56
	global_store_dword v[22:23], v56, off offset:2048
	v_add_f32_e32 v57, s38, v57
	v_readlane_b32 s38, v64, 26
	v_mul_f32_e32 v57, 0x3fb8aa3b, v57
	global_store_dword v[22:23], v57, off offset:2304
	v_add_f32_e32 v58, s33, v58
	v_readlane_b32 s33, v64, 27
	v_mul_f32_e32 v58, 0x3fb8aa3b, v58
	global_store_dword v[22:23], v58, off offset:2560
	v_add_f32_e32 v59, s38, v59
	v_readlane_b32 s38, v64, 28
	v_mul_f32_e32 v59, 0x3fb8aa3b, v59
	global_store_dword v[22:23], v59, off offset:2816
	v_add_f32_e32 v60, s33, v60
	v_readlane_b32 s33, v64, 29
	v_mul_f32_e32 v60, 0x3fb8aa3b, v60
	global_store_dword v[22:23], v60, off offset:3072
	v_add_f32_e32 v61, s38, v61
	v_readlane_b32 s38, v64, 30
	v_mul_f32_e32 v61, 0x3fb8aa3b, v61
	global_store_dword v[22:23], v61, off offset:3328
	v_add_f32_e32 v62, s33, v62
	v_mul_f32_e32 v62, 0x3fb8aa3b, v62
	global_store_dword v[22:23], v62, off offset:3584
	v_add_f32_e32 v63, s38, v63
	v_mul_f32_e32 v63, 0x3fb8aa3b, v63
	global_store_dword v[22:23], v63, off offset:3840
	s_branch .LBB0_658
